# v03 (branch epi + gla_job global loads) + CVX 5000->7680 (more layer-1 w_in conversion by the sample team, shorter branch tail)
# baseline (speedup 1.0000x reference)
.LBB0_80:
	v_readlane_b32 s22, v248, 1
	v_readlane_b32 s23, v248, 2
	s_add_u32 s0, s22, 0x72d00000
	s_addc_u32 s1, s23, 0
	v_writelane_b32 v249, s0, 4
	v_readlane_b32 s24, v248, 7
	v_readlane_b32 s48, v248, 26
	v_writelane_b32 v249, s1, 5
	s_ashr_i32 s0, s24, 31
	v_readlane_b32 s50, v248, 28
	v_writelane_b32 v249, s0, 6
	v_readlane_b32 s51, v248, 29
	s_add_u32 s0, s50, 0x2000
	s_addc_u32 s1, s51, 0
	v_writelane_b32 v249, s0, 7
	s_cmpk_lg_i32 s24, 0x100
	v_readlane_b32 s13, v248, 43
	v_writelane_b32 v249, s1, 8
	s_cselect_b64 s[0:1], -1, 0
	v_writelane_b32 v249, s0, 9
	s_cmpk_lt_i32 s13, 0x1400
	v_readlane_b32 s21, v248, 0
	v_writelane_b32 v249, s1, 10
	s_cselect_b64 s[0:1], -1, 0
	v_writelane_b32 v249, s0, 11
	v_readlane_b32 s49, v248, 27
	v_mov_b32_e32 v34, 0
	v_writelane_b32 v249, s1, 12
	s_add_i32 s0, s13, 0x3c80
	s_add_u32 s9, s22, 0x24500000
	s_addc_u32 s12, s23, 0
	s_add_u32 s5, s22, 0x1e500000
	v_writelane_b32 v249, s0, 13
	s_addc_u32 s11, s23, 0
	s_add_i32 s0, s21, 0xffffff97
	s_cmpk_lt_u32 s0, 0x67
	s_cselect_b64 s[0:1], -1, 0
	v_writelane_b32 v249, s0, 14
	v_mov_b32_e32 v219, 1
	v_mov_b32_e32 v222, 0x358637bd
	v_writelane_b32 v249, s1, 15
	s_add_i32 s0, s13, 0xfffffcb8
	s_cmpk_lt_i32 s0, 0x1400
	s_cselect_b64 s[0:1], -1, 0
	v_writelane_b32 v249, s0, 16
	v_mov_b32_e32 v223, 0x260
	v_mov_b32_e32 v224, 0x3ecc95a3
	v_writelane_b32 v249, s1, 17
	s_add_i32 s0, s13, 0x3938
	v_writelane_b32 v249, s0, 18
	s_add_u32 s0, s22, 0x4200
	s_addc_u32 s1, s23, 0
	v_writelane_b32 v249, s0, 19
	v_mov_b32_e32 v225, 0x3e2aaaab
	v_mov_b64_e32 v[164:165], 0x969
	v_writelane_b32 v249, s1, 20
	s_add_u32 s0, s22, 0x4400
	s_addc_u32 s1, s23, 0
	v_writelane_b32 v249, s0, 21
	v_mov_b64_e32 v[166:167], 0x968
	v_mov_b32_e32 v226, 0x41b17218
	v_writelane_b32 v249, s1, 22
	s_add_u32 s0, s22, 0x4500
	s_addc_u32 s1, s23, 0
	v_writelane_b32 v249, s0, 23
	v_mov_b64_e32 v[168:169], 0x630
	v_mov_b64_e32 v[170:171], 0x62f
	v_writelane_b32 v249, s1, 24
	s_add_u32 s0, s22, 0x4600
	s_addc_u32 s1, s23, 0
	v_writelane_b32 v249, s0, 25
	v_mov_b32_e32 v227, 0x1e040
	v_mov_b32_e32 v228, 2
	v_writelane_b32 v249, s1, 26
	s_add_u32 s0, s22, 0x4700
	s_addc_u32 s1, s23, 0
	v_writelane_b32 v249, s0, 27
	v_mov_b32_e32 v230, 0x3000
	v_mov_b32_e32 v231, 0x7f800000
	v_writelane_b32 v249, s1, 28
	s_add_u32 s0, s22, 0x4800
	s_addc_u32 s1, s23, 0
	v_writelane_b32 v249, s0, 29
	v_readlane_b32 s52, v248, 30
	v_readlane_b32 s53, v248, 31
	v_writelane_b32 v249, s1, 30
	s_add_u32 s0, s22, 0x4900
	s_addc_u32 s1, s23, 0
	v_writelane_b32 v249, s0, 31
	v_readlane_b32 s54, v248, 32
	v_readlane_b32 s55, v248, 33
	v_writelane_b32 v249, s1, 32
	s_add_u32 s0, s22, 0x4a00
	s_addc_u32 s1, s23, 0
	v_writelane_b32 v249, s0, 33
	v_readlane_b32 s56, v248, 34
	v_readlane_b32 s57, v248, 35
	v_writelane_b32 v249, s1, 34
	s_add_u32 s0, s22, 0x4b00
	s_addc_u32 s1, s23, 0
	v_writelane_b32 v249, s0, 35
	v_readlane_b32 s58, v248, 36
	v_readlane_b32 s59, v248, 37
	v_writelane_b32 v249, s1, 36
	s_add_u32 s0, s22, 0x4c00
	s_addc_u32 s1, s23, 0
	v_writelane_b32 v249, s0, 37
	v_readlane_b32 s60, v248, 38
	v_readlane_b32 s61, v248, 39
	v_writelane_b32 v249, s1, 38
	s_add_u32 s0, s22, 0x4d00
	s_addc_u32 s1, s23, 0
	v_writelane_b32 v249, s0, 39
	v_readlane_b32 s62, v248, 40
	v_readlane_b32 s63, v248, 41
	v_writelane_b32 v249, s1, 40
	s_add_u32 s0, s22, 0x4e00
	s_addc_u32 s1, s23, 0
	v_writelane_b32 v249, s0, 41
	s_nop 1
	v_writelane_b32 v249, s1, 42
	s_add_u32 s0, s22, 0x4f00
	s_addc_u32 s1, s23, 0
	v_writelane_b32 v249, s0, 43
	s_nop 1
	v_writelane_b32 v249, s1, 44
	s_add_u32 s0, s22, 0x5000
	s_addc_u32 s1, s23, 0
	v_writelane_b32 v249, s0, 45
	s_nop 1
	v_writelane_b32 v249, s1, 46
	s_add_u32 s0, s22, 0x5100
	s_addc_u32 s1, s23, 0
	v_writelane_b32 v249, s0, 47
	s_nop 1
	v_writelane_b32 v249, s1, 48
	s_add_u32 s0, s22, 0x5200
	s_addc_u32 s1, s23, 0
	v_writelane_b32 v249, s0, 49
	s_nop 1
	v_writelane_b32 v249, s1, 50
	s_add_u32 s0, s22, 0x5300
	s_addc_u32 s1, s23, 0
	v_writelane_b32 v249, s0, 51
	s_cmp_eq_u32 s46, 15
	s_nop 0
	v_writelane_b32 v249, s1, 52
	s_cselect_b64 s[0:1], -1, 0
	v_writelane_b32 v249, s0, 53
	s_cmp_eq_u32 s46, 14
	s_nop 0
	v_writelane_b32 v249, s1, 54
	s_cselect_b64 s[0:1], -1, 0
	v_writelane_b32 v249, s0, 55
	s_cmp_eq_u32 s46, 13
	s_nop 0
	v_writelane_b32 v249, s1, 56
	s_cselect_b64 s[0:1], -1, 0
	v_writelane_b32 v249, s0, 57
	s_cmp_eq_u32 s46, 12
	s_nop 0
	v_writelane_b32 v249, s1, 58
	s_cselect_b64 s[0:1], -1, 0
	v_writelane_b32 v249, s0, 59
	s_cmp_eq_u32 s46, 11
	s_nop 0
	v_writelane_b32 v249, s1, 60
	s_cselect_b64 s[0:1], -1, 0
	v_writelane_b32 v249, s0, 61
	s_cmp_eq_u32 s46, 10
	s_nop 0
	v_writelane_b32 v249, s1, 62
	s_cselect_b64 s[0:1], -1, 0
	v_writelane_b32 v249, s0, 63
	s_cmp_eq_u32 s46, 9
	s_nop 0
	v_writelane_b32 v250, s1, 0
	s_cselect_b64 s[0:1], -1, 0
	v_writelane_b32 v250, s0, 1
	s_cmp_eq_u32 s46, 8
	s_nop 0
	v_writelane_b32 v250, s1, 2
	s_cselect_b64 s[0:1], -1, 0
	v_writelane_b32 v250, s0, 3
	s_cmp_eq_u32 s46, 7
	s_nop 0
	v_writelane_b32 v250, s1, 4
	s_cselect_b64 s[0:1], -1, 0
	v_writelane_b32 v250, s0, 5
	s_cmp_eq_u32 s46, 6
	s_nop 0
	v_writelane_b32 v250, s1, 6
	s_cselect_b64 s[0:1], -1, 0
	v_writelane_b32 v250, s0, 7
	s_cmp_eq_u32 s46, 5
	s_nop 0
	v_writelane_b32 v250, s1, 8
	s_cselect_b64 s[0:1], -1, 0
	v_writelane_b32 v250, s0, 9
	s_cmp_eq_u32 s46, 4
	s_nop 0
	v_writelane_b32 v250, s1, 10
	s_cselect_b64 s[0:1], -1, 0
	v_writelane_b32 v250, s0, 11
	s_cmp_eq_u32 s46, 3
	s_nop 0
	v_writelane_b32 v250, s1, 12
	s_cselect_b64 s[0:1], -1, 0
	v_writelane_b32 v250, s0, 13
	s_cmp_eq_u32 s46, 2
	s_nop 0
	v_writelane_b32 v250, s1, 14
	s_cselect_b64 s[0:1], -1, 0
	v_writelane_b32 v250, s0, 15
	s_cmp_eq_u32 s46, 1
	s_nop 0
	v_writelane_b32 v250, s1, 16
	s_cselect_b64 s[0:1], -1, 0
	v_writelane_b32 v250, s0, 17
	s_cmp_eq_u32 s46, 0
	s_nop 0
	v_writelane_b32 v250, s1, 18
	s_cselect_b64 s[0:1], -1, 0
	v_writelane_b32 v250, s0, 19
	s_nop 1
	v_writelane_b32 v250, s1, 20
	s_lshl_b32 s0, s46, 8
	s_add_u32 s0, s2, s0
	s_addc_u32 s1, s3, 0
	s_add_u32 s2, s0, 0x1400
	s_addc_u32 s3, s1, 0
	v_writelane_b32 v250, s2, 21
	s_add_u32 s0, s0, 0x2400
	s_addc_u32 s1, s1, 0
	v_writelane_b32 v250, s3, 22
	v_writelane_b32 v250, s0, 23
	s_nop 1
	v_writelane_b32 v250, s1, 24
	s_add_u32 s0, s22, 0x7400
	s_addc_u32 s1, s23, 0
	v_writelane_b32 v250, s0, 25
	s_nop 1
	v_writelane_b32 v250, s1, 26
	s_add_u32 s0, s22, 0x7500
	s_addc_u32 s1, s23, 0
	v_writelane_b32 v250, s0, 27
	s_cmpk_lt_i32 s21, 0x220
	s_nop 0
	v_writelane_b32 v250, s1, 28
	s_cselect_b64 s[0:1], -1, 0
	v_writelane_b32 v250, s0, 29
	s_ashr_i32 s14, s21, 31
	s_add_i32 s8, s21, 0xffffff40
	v_writelane_b32 v250, s1, 30
	s_lshr_b32 s0, s14, 26
	s_add_i32 s0, s21, s0
	s_ashr_i32 s7, s0, 6
	s_add_i32 s0, s24, 0xffffff40
	v_writelane_b32 v250, s0, 31
	s_sub_i32 s0, s21, 64
	s_cmpk_lt_i32 s21, 0x80
	s_cselect_b32 s25, s21, s0
	s_cmpk_lt_i32 s25, 0x220
	v_writelane_b32 v250, s0, 32
	s_cselect_b64 s[0:1], -1, 0
	v_writelane_b32 v250, s0, 33
	s_nop 1
	v_writelane_b32 v250, s1, 34
	s_add_u32 s0, s22, 0x12000
	v_writelane_b32 v250, s0, 35
	s_addc_u32 s0, s23, 0
	v_writelane_b32 v250, s0, 36
	s_add_i32 s0, s21, 0xffffff80
	v_writelane_b32 v250, s0, 37
	s_add_i32 s0, s21, 1
	v_writelane_b32 v250, s0, 38
	s_sub_i32 s0, s21, 63
	v_writelane_b32 v250, s0, 39
	s_add_i32 s0, s21, 0xffffff81
	s_cmpk_gt_i32 s21, 0xbf
	v_writelane_b32 v250, s0, 40
	s_cselect_b64 s[0:1], -1, 0
	s_cmpk_eq_i32 s24, 0x100
	s_cselect_b64 s[26:27], -1, 0
	s_and_b64 s[2:3], s[26:27], exec
	s_movk_i32 s2, 0x200
	s_cselect_b32 s6, s2, 0x210
	s_movk_i32 s2, 0x2000
	s_cselect_b32 s2, s2, 0x2100
	v_writelane_b32 v250, s2, 41
	s_cselect_b32 s19, 32, 33
	s_cselect_b32 s10, 0x1e00, 0
	s_and_b64 s[0:1], s[0:1], s[26:27]
	v_writelane_b32 v250, s0, 42
	s_nop 1
	v_writelane_b32 v250, s1, 43
	s_add_u32 s0, s22, 0x10000
	v_writelane_b32 v250, s0, 44
	s_addc_u32 s0, s23, 0
	v_writelane_b32 v250, s0, 45
	s_lshl_b32 s0, s8, 3
	s_add_i32 s15, s33, s0
	s_cmpk_lt_i32 s21, 0xf0
	s_mul_hi_i32 s0, s8, 0x55555556
	s_cselect_b64 s[2:3], -1, 0
	s_lshr_b32 s1, s0, 31
	s_add_i32 s1, s0, s1
	s_mul_i32 s0, s1, -3
	v_writelane_b32 v250, s2, 46
	s_add_i32 s0, s0, s8
	s_mul_i32 s4, s1, 0x300000
	v_writelane_b32 v250, s3, 47
	s_lshl_b32 s2, s0, 11
	s_ashr_i32 s3, s2, 31
	s_lshl_b64 s[28:29], s[2:3], 1
	s_add_u32 s2, s5, s28
	v_writelane_b32 v250, s5, 48
	s_addc_u32 s3, s11, s29
	v_writelane_b32 v250, s11, 49
	s_add_u32 s2, s2, s4
	s_mul_hi_i32 s5, s1, 0x300000
	v_writelane_b32 v250, s2, 50
	s_addc_u32 s2, s3, s5
	v_writelane_b32 v250, s2, 51
	s_lshl_b32 s1, s1, 8
	v_writelane_b32 v250, s1, 52
	s_ashr_i32 s1, s0, 31
	s_lshl_b64 s[2:3], s[0:1], 12
	v_writelane_b32 v250, s2, 53
	s_lshl_b64 s[0:1], s[0:1], 22
	s_ashr_i32 s8, s8, 2
	v_writelane_b32 v250, s3, 54
	v_writelane_b32 v250, s0, 55
	s_nop 1
	v_writelane_b32 v250, s1, 56
	s_and_b32 s0, s21, 3
	s_lshl_b32 s2, s0, 10
	s_lshl_b32 s30, s0, 11
	v_writelane_b32 v250, s9, 57
	s_add_u32 s11, s9, s30
	v_writelane_b32 v250, s12, 58
	s_addc_u32 s12, s12, 0
	s_ashr_i32 s9, s8, 31
	s_lshl_b32 s3, s0, 20
	s_lshl_b64 s[0:1], s[8:9], 21
	s_add_u32 s9, s11, s0
	v_writelane_b32 v250, s9, 59
	s_addc_u32 s9, s12, s1
	v_writelane_b32 v250, s9, 60
	s_lshl_b32 s8, s8, 8
	v_writelane_b32 v250, s8, 61
	s_cmpk_lt_i32 s15, 0x1e00
	v_writelane_b32 v250, s15, 62
	s_cselect_b64 s[8:9], -1, 0
	v_writelane_b32 v250, s8, 63
	s_nop 1
	v_writelane_b32 v251, s9, 0
	s_add_u32 s8, s48, 0x1e040000
	s_addc_u32 s9, s49, 0
	v_writelane_b32 v251, s8, 1
	v_readlane_b32 s36, v248, 10
	v_readlane_b32 s50, v248, 24
	v_writelane_b32 v251, s9, 2
	s_add_u32 s8, s22, 0xf300000
	s_addc_u32 s9, s23, 0
	s_lshl_b32 s34, s19, 4
	v_writelane_b32 v251, s8, 3
	s_cmp_lt_i32 s21, s34
	v_readlane_b32 s51, v248, 25
	v_writelane_b32 v251, s9, 4
	s_cselect_b64 s[8:9], -1, 0
	v_writelane_b32 v251, s8, 5
	s_add_i32 s16, s24, s6
	s_add_i32 s20, s19, -8
	v_writelane_b32 v251, s9, 6
	s_lshr_b32 s8, s14, 29
	s_add_i32 s8, s21, s8
	v_writelane_b32 v251, s14, 7
	s_ashr_i32 s14, s8, 3
	s_and_b32 s8, s8, -8
	s_sub_i32 s15, s21, s8
	s_add_i32 s17, s16, -1
	s_add_i32 s8, s13, s10
	s_cmpk_lt_i32 s8, 0x3c80
	v_writelane_b32 v251, s8, 8
	s_cselect_b64 s[8:9], -1, 0
	v_writelane_b32 v251, s8, 9
	v_readlane_b32 s48, v248, 22
	v_readlane_b32 s49, v248, 23
	v_writelane_b32 v251, s9, 10
	s_add_u32 s8, s22, 0x85300000
	s_addc_u32 s9, s23, 0
	s_lshl_b32 s31, s19, 1
	v_writelane_b32 v251, s8, 11
	s_add_i32 s18, s10, s33
	s_or_b32 s33, s31, 1
	v_writelane_b32 v251, s9, 12
	s_add_u32 s8, s22, 0x76d00000
	v_writelane_b32 v251, s8, 13
	s_addc_u32 s8, s23, 0
	v_writelane_b32 v251, s8, 14
	s_add_u32 s8, s50, 0x4000
	s_addc_u32 s9, s51, 0
	v_writelane_b32 v251, s8, 15
	v_mov_b32_e32 v1, s15
	v_alignbit_b32 v1, s19, v1, 31
	v_writelane_b32 v251, s9, 16
	s_add_u32 s8, s48, 0x4000
	s_addc_u32 s9, s49, 0
	v_writelane_b32 v251, s8, 17
	v_readlane_b32 s37, v248, 11
	v_readlane_b32 s38, v248, 12
	v_writelane_b32 v251, s9, 18
	v_readlane_b32 s8, v248, 3
	v_readlane_b32 s9, v248, 4
	s_mov_b64 s[12:13], s[8:9]
	s_cmp_gt_i32 s12, 7
	v_readlane_b32 s10, v248, 5
	v_readlane_b32 s11, v248, 6
	s_cselect_b64 s[8:9], -1, 0
	s_cmp_lt_i32 s13, 9
	s_cselect_b64 s[10:11], -1, 0
	s_cmpk_lt_i32 s21, 0xc0
	s_cselect_b32 s7, s7, -1
	s_cmpk_gt_i32 s24, 0xc0
	s_cselect_b32 s7, s7, -2
	s_cmp_lg_u32 s7, 2
	s_cselect_b64 s[12:13], -1, 0
	v_writelane_b32 v251, s26, 19
	s_and_b64 s[12:13], s[26:27], s[12:13]
	s_cmp_lg_u32 s7, 1
	v_writelane_b32 v251, s27, 20
	v_writelane_b32 v251, s12, 21
	v_readlane_b32 s39, v248, 13
	v_readlane_b32 s40, v248, 14
	v_writelane_b32 v251, s13, 22
	v_writelane_b32 v251, s7, 23
	v_readfirstlane_b32 s7, v1
	v_writelane_b32 v251, s19, 24
	s_mul_i32 s7, s7, s15
	s_cselect_b64 s[12:13], -1, 0
	v_writelane_b32 v251, s12, 25
	s_add_i32 s7, s7, s14
	v_readlane_b32 s41, v248, 15
	v_writelane_b32 v251, s13, 26
	s_ashr_i32 s12, s7, 31
	s_lshr_b32 s12, s12, 25
	s_add_i32 s12, s7, s12
	s_ashr_i32 s12, s12, 7
	s_lshl_b32 s13, s12, 7
	s_sub_i32 s7, s7, s13
	s_lshl_b32 s12, s12, 3
	s_cmp_gt_i32 s12, s20
	s_cselect_b32 s13, 1, 8
	s_cmp_lt_i32 s15, 0
	s_cselect_b32 s19, s33, s31
	s_mul_i32 s15, s19, s15
	s_add_i32 s14, s15, s14
	v_cvt_f32_ubyte0_e32 v1, s13
	s_ashr_i32 s15, s14, 31
	v_rcp_iflag_f32_e32 v1, v1
	s_lshr_b32 s15, s15, 25
	s_add_i32 s15, s14, s15
	s_ashr_i32 s15, s15, 7
	s_lshl_b32 s19, s15, 7
	v_mul_f32_e32 v1, 0x4f7ffffe, v1
	v_writelane_b32 v251, s31, 27
	s_sub_i32 s14, s14, s19
	s_lshl_b32 s15, s15, 3
	v_cvt_u32_f32_e32 v1, v1
	v_writelane_b32 v251, s33, 28
	s_cmp_gt_i32 s15, s20
	v_writelane_b32 v251, s20, 29
	s_cselect_b32 s19, 1, 8
	s_or_b64 s[8:9], s[8:9], s[10:11]
	v_writelane_b32 v251, s8, 30
	s_mov_b32 s33, 0xbcf5c28f
	v_readlane_b32 s42, v248, 16
	v_writelane_b32 v251, s9, 31
	s_sub_i32 s8, 0, s13
	v_readfirstlane_b32 s9, v1
	s_mul_i32 s8, s8, s9
	s_mul_hi_u32 s8, s9, s8
	s_add_i32 s9, s9, s8
	s_abs_i32 s8, s7
	s_mul_hi_u32 s9, s8, s9
	s_mul_i32 s10, s9, s13
	s_sub_i32 s8, s8, s10
	s_ashr_i32 s10, s7, 31
	s_add_i32 s11, s9, 1
	s_sub_i32 s20, s8, s13
	s_cmp_ge_u32 s8, s13
	s_cselect_b32 s9, s11, s9
	s_cselect_b32 s8, s20, s8
	s_add_i32 s11, s9, 1
	s_cmp_ge_u32 s8, s13
	s_cselect_b32 s8, s11, s9
	s_xor_b32 s8, s8, s10
	s_sub_i32 s8, s8, s10
	v_writelane_b32 v251, s8, 32
	s_mul_i32 s8, s8, s13
	s_sub_i32 s7, s7, s8
	s_add_i32 s7, s12, s7
	v_writelane_b32 v251, s7, 33
	s_abs_i32 s7, s24
	v_cvt_f32_u32_e32 v1, s7
	s_sub_i32 s8, 0, s7
	v_readlane_b32 s43, v248, 17
	v_readlane_b32 s44, v248, 18
	v_rcp_iflag_f32_e32 v1, v1
	v_readlane_b32 s45, v248, 19
	v_readlane_b32 s46, v248, 20
	v_readlane_b32 s47, v248, 21
	v_mul_f32_e32 v1, 0x4f7ffffe, v1
	v_cvt_u32_f32_e32 v1, v1
	s_nop 0
	v_readfirstlane_b32 s9, v1
	s_mul_i32 s8, s8, s9
	s_mul_hi_u32 s8, s9, s8
	s_add_i32 s9, s9, s8
	s_sub_i32 s8, 1, s16
	s_max_i32 s8, s17, s8
	s_mul_hi_u32 s9, s8, s9
	s_mul_i32 s10, s9, s7
	s_sub_i32 s8, s8, s10
	s_xor_b32 s10, s17, s24
	s_ashr_i32 s10, s10, 31
	s_add_i32 s11, s9, 1
	s_sub_i32 s12, s8, s7
	s_cmp_ge_u32 s8, s7
	s_cselect_b32 s9, s11, s9
	s_cselect_b32 s8, s12, s8
	s_add_i32 s11, s9, 1
	s_cmp_ge_u32 s8, s7
	s_cselect_b32 s7, s11, s9
	s_xor_b32 s7, s7, s10
	s_not_b32 s8, s10
	s_add_i32 s7, s8, s7
	s_mul_i32 s7, s7, s24
	s_sub_i32 s6, s6, s7
	s_sub_i32 s7, s24, s6
	v_cvt_f32_ubyte0_e32 v1, s19
	s_cmp_lt_i32 s7, 1
	v_rcp_iflag_f32_e32 v1, v1
	s_cselect_b64 s[8:9], -1, 0
	v_writelane_b32 v251, s8, 34
	s_cmp_ge_i32 s21, s6
	v_mul_f32_e32 v1, 0x4f7ffffe, v1
	v_writelane_b32 v251, s9, 35
	s_cselect_b64 s[8:9], -1, 0
	s_sub_i32 s6, s21, s6
	v_writelane_b32 v251, s8, 36
	s_lshl_b32 s6, s6, 3
	s_add_i32 s6, s18, s6
	v_writelane_b32 v251, s9, 37
	s_lshl_b32 s7, s7, 3
	v_cvt_u32_f32_e32 v1, v1
	v_writelane_b32 v251, s7, 38
	s_cmpk_lt_i32 s6, 0x3c80
	v_writelane_b32 v251, s6, 39
	s_cselect_b64 s[6:7], -1, 0
	v_writelane_b32 v251, s6, 40
	s_nop 1
	v_writelane_b32 v251, s7, 41
	s_sub_i32 s6, 0, s19
	v_readfirstlane_b32 s7, v1
	s_mul_i32 s6, s6, s7
	s_mul_hi_u32 s6, s7, s6
	s_add_i32 s7, s7, s6
	s_abs_i32 s6, s14
	s_mul_hi_u32 s7, s6, s7
	s_mul_i32 s8, s7, s19
	s_sub_i32 s6, s6, s8
	s_ashr_i32 s8, s14, 31
	s_add_i32 s9, s7, 1
	s_sub_i32 s10, s6, s19
	s_cmp_ge_u32 s6, s19
	s_cselect_b32 s7, s9, s7
	s_cselect_b32 s6, s10, s6
	s_add_i32 s9, s7, 1
	s_cmp_ge_u32 s6, s19
	s_cselect_b32 s6, s9, s7
	s_xor_b32 s6, s6, s8
	s_sub_i32 s8, s6, s8
	s_mul_i32 s6, s8, s19
	s_sub_i32 s6, s14, s6
	s_add_i32 s10, s15, s6
	s_lshl_b32 s6, s21, 8
	v_writelane_b32 v251, s6, 42
	s_lshl_b32 s6, s24, 8
	v_writelane_b32 v251, s6, 43
	v_writelane_b32 v251, s25, 44
	s_lshl_b32 s6, s25, 8
	v_writelane_b32 v251, s6, 45
	s_mov_b32 s6, s10
	s_ashr_i32 s11, s10, 31
	v_writelane_b32 v251, s6, 46
	s_ashr_i32 s9, s8, 31
	v_mbcnt_lo_u32_b32 v1, -1, 0
	v_writelane_b32 v251, s7, 47
	s_lshl_b64 s[6:7], s[10:11], 21
	v_writelane_b32 v251, s6, 48
	v_mbcnt_hi_u32_b32 v229, -1, v1
	s_nop 0
	v_writelane_b32 v251, s7, 49
	s_mov_b32 s6, s8
	v_writelane_b32 v251, s6, 50
	s_nop 1
	v_writelane_b32 v251, s7, 51
	s_lshl_b64 s[6:7], s[8:9], 21
	s_add_u32 s4, s4, s28
	s_addc_u32 s5, s5, s29
	s_add_u32 s4, s22, s4
	v_writelane_b32 v251, s6, 52
	s_addc_u32 s5, s23, s5
	s_add_u32 s4, s4, 0x1e500100
	v_writelane_b32 v251, s7, 53
	v_writelane_b32 v251, s4, 54
	s_addc_u32 s4, s5, 0
	v_writelane_b32 v251, s4, 55
	s_add_u32 s4, s28, 0x55b80080
	v_writelane_b32 v251, s4, 56
	v_writelane_b32 v251, s28, 57
	s_addc_u32 s4, s29, 0
	s_or_b32 s0, s0, s30
	v_writelane_b32 v251, s29, 58
	s_mov_b32 s5, 0
	v_writelane_b32 v251, s4, 59
	s_add_u32 s0, s22, s0
	s_mov_b32 s35, s5
	s_addc_u32 s1, s23, s1
	v_writelane_b32 v251, s34, 60
	s_add_u32 s0, s0, 0x24500100
	s_mov_b64 s[6:7], -1
	v_writelane_b32 v251, s35, 61
	v_writelane_b32 v251, s0, 62
	s_addc_u32 s0, s1, 0
	v_writelane_b32 v251, s0, 63
	s_mul_hi_i32 s1, s66, 0x3000
	s_mul_i32 s0, s66, 0x3000
	v_writelane_b32 v252, s0, 0
	s_ashr_i32 s67, s66, 31
	s_mov_b32 s12, s5
	v_writelane_b32 v252, s1, 1
	s_lshl_b32 s0, s2, 1
	v_writelane_b32 v252, s0, 2
	s_lshl_b32 s0, s3, 2
	v_writelane_b32 v252, s0, 3
	v_writelane_b32 v252, s30, 4
	s_or_b32 s0, s30, 0x6a800080
	v_writelane_b32 v252, s0, 5
	s_add_i32 s0, 0, 0x19800
	v_writelane_b32 v252, s0, 6
	v_cmp_eq_u32_e64 s[0:1], 0, v0
	s_mov_b64 s[2:3], 0x80
	s_nop 0
	v_writelane_b32 v252, s0, 7
	s_nop 1
	v_writelane_b32 v252, s1, 8
	s_lshl_b64 s[0:1], s[66:67], 12
	v_writelane_b32 v252, s0, 9
	s_nop 1
	v_writelane_b32 v252, s1, 10
	s_lshl_b64 s[0:1], s[66:67], 7
	v_writelane_b32 v252, s0, 11
	s_nop 1
	v_writelane_b32 v252, s1, 12
	s_lshl_b64 s[0:1], s[66:67], 13
	v_writelane_b32 v252, s0, 13
	s_nop 1
	v_writelane_b32 v252, s1, 14
	s_mov_b32 s1, 0
	v_writelane_b32 v252, s0, 15
	s_nop 1
	v_writelane_b32 v252, s1, 16
	v_writelane_b32 v252, s66, 17
	s_nop 1
	v_writelane_b32 v252, s67, 18
	s_branch .LBB0_84

.LBB0_1497:
	s_or_b64 exec, exec, s[4:5]
	v_readfirstlane_b32 s4, v0
	s_lshl_b32 s4, s4, 8
	s_and_b32 s4, s4, 0x7fffc000
	s_add_i32 s4, s4, 0
	v_add_u32_e32 v1, s4, v134
	s_waitcnt vmcnt(0)
	v_cvt_pk_bf16_f32 v139, v6, v4
	v_cvt_pk_bf16_f32 v4, v11, v9
	v_cvt_pk_bf16_f32 v5, v7, v5
	v_cvt_pk_bf16_f32 v6, v25, v21
	v_cvt_pk_bf16_f32 v7, v17, v13
	ds_write_b128 v1, v[4:7] offset:128
	v_cvt_pk_bf16_f32 v4, v27, v23
	v_cvt_pk_bf16_f32 v5, v19, v15
	v_cvt_pk_bf16_f32 v6, v43, v39
	v_cvt_pk_bf16_f32 v7, v33, v29
	v_cvt_pk_bf16_f32 v138, v10, v8
	v_cvt_pk_bf16_f32 v140, v24, v20
	v_cvt_pk_bf16_f32 v141, v16, v12
	ds_write_b128 v1, v[4:7] offset:144
	v_cvt_pk_bf16_f32 v4, v45, v41
	v_cvt_pk_bf16_f32 v5, v37, v31
	v_cvt_pk_bf16_f32 v6, v59, v55
	v_cvt_pk_bf16_f32 v7, v51, v47
	ds_write_b128 v1, v[138:141]
	v_cvt_pk_bf16_f32 v138, v26, v22
	v_cvt_pk_bf16_f32 v139, v18, v14
	v_cvt_pk_bf16_f32 v140, v42, v38
	v_cvt_pk_bf16_f32 v141, v32, v28
	ds_write_b128 v1, v[4:7] offset:160
	v_cvt_pk_bf16_f32 v4, v61, v57
	v_cvt_pk_bf16_f32 v5, v53, v49
	v_cvt_pk_bf16_f32 v6, v75, v71
	v_cvt_pk_bf16_f32 v7, v67, v63
	ds_write_b128 v1, v[138:141] offset:16
	v_cvt_pk_bf16_f32 v138, v44, v40
	v_cvt_pk_bf16_f32 v139, v36, v30
	v_cvt_pk_bf16_f32 v140, v58, v54
	v_cvt_pk_bf16_f32 v141, v50, v46
	ds_write_b128 v1, v[4:7] offset:176
	v_cvt_pk_bf16_f32 v4, v77, v73
	v_cvt_pk_bf16_f32 v5, v69, v65
	v_cvt_pk_bf16_f32 v6, v91, v87
	v_cvt_pk_bf16_f32 v7, v83, v79
	ds_write_b128 v1, v[138:141] offset:32
	v_cvt_pk_bf16_f32 v138, v60, v56
	v_cvt_pk_bf16_f32 v139, v52, v48
	v_cvt_pk_bf16_f32 v140, v74, v70
	v_cvt_pk_bf16_f32 v141, v66, v62
	ds_write_b128 v1, v[4:7] offset:192
	v_cvt_pk_bf16_f32 v4, v93, v89
	v_cvt_pk_bf16_f32 v5, v85, v81
	v_cvt_pk_bf16_f32 v6, v107, v103
	v_cvt_pk_bf16_f32 v7, v99, v95
	ds_write_b128 v1, v[138:141] offset:48
	v_cvt_pk_bf16_f32 v138, v76, v72
	v_cvt_pk_bf16_f32 v139, v68, v64
	v_cvt_pk_bf16_f32 v140, v90, v86
	v_cvt_pk_bf16_f32 v141, v82, v78
	ds_write_b128 v1, v[4:7] offset:208
	v_cvt_pk_bf16_f32 v4, v109, v105
	v_cvt_pk_bf16_f32 v5, v101, v97
	v_cvt_pk_bf16_f32 v6, v123, v119
	v_cvt_pk_bf16_f32 v7, v115, v111
	ds_write_b128 v1, v[138:141] offset:64
	v_cvt_pk_bf16_f32 v138, v92, v88
	v_cvt_pk_bf16_f32 v139, v84, v80
	v_cvt_pk_bf16_f32 v140, v106, v102
	v_cvt_pk_bf16_f32 v141, v98, v94
	ds_write_b128 v1, v[4:7] offset:224
	v_cvt_pk_bf16_f32 v4, v125, v121
	v_cvt_pk_bf16_f32 v5, v117, v113
	v_cvt_pk_bf16_f32 v6, v133, v131
	v_cvt_pk_bf16_f32 v7, v129, v127
	ds_write_b128 v1, v[138:141] offset:80
	v_cvt_pk_bf16_f32 v138, v108, v104
	v_cvt_pk_bf16_f32 v139, v100, v96
	v_cvt_pk_bf16_f32 v140, v122, v118
	v_cvt_pk_bf16_f32 v141, v114, v110
	ds_write_b128 v1, v[4:7] offset:240
	v_add_u32_e32 v4, s8, v135
	ds_write_b128 v1, v[138:141] offset:96
	v_cvt_pk_bf16_f32 v138, v124, v120
	v_cvt_pk_bf16_f32 v139, v116, v112
	v_cvt_pk_bf16_f32 v140, v132, v130
	v_cvt_pk_bf16_f32 v141, v128, v126
	v_ashrrev_i32_e32 v5, 31, v4
	v_readlane_b32 s8, v251, 3
	ds_write_b128 v1, v[138:141] offset:112
	v_lshlrev_b64 v[4:5], 13, v[4:5]
	v_readlane_b32 s9, v251, 4
	v_add_u32_e32 v1, s4, v136
	v_mov_b32_e32 v3, v34
	v_lshl_add_u64 v[8:9], s[8:9], 0, v[4:5]
	ds_read_b128 v[4:7], v1
	v_lshl_add_u64 v[8:9], s[0:1], 1, v[8:9]
	v_lshl_add_u64 v[12:13], v[8:9], 0, v[2:3]
	ds_read_b128 v[8:11], v1 offset:1024
	s_mov_b32 s0, 0x10000
	s_waitcnt lgkmcnt(0)
	global_store_dwordx4 v[12:13], v[4:7], off
	s_add_i32 s6, s6, 0x10000
	s_nop 0
	v_add_co_u32_e32 v4, vcc, s0, v12
	s_mov_b32 s0, 0x20000
	s_nop 0
	v_addc_co_u32_e32 v5, vcc, 0, v13, vcc
	global_store_dwordx4 v[4:5], v[8:11], off
	ds_read_b128 v[4:7], v1 offset:2048
	ds_read_b128 v[8:11], v1 offset:3072
	v_add_co_u32_e32 v14, vcc, s0, v12
	s_mov_b32 s0, 0x30000
	s_nop 0
	v_addc_co_u32_e32 v15, vcc, 0, v13, vcc
	s_waitcnt lgkmcnt(1)
	global_store_dwordx4 v[14:15], v[4:7], off
	s_nop 1
	v_add_co_u32_e32 v4, vcc, s0, v12
	s_mov_b32 s0, 0x40000
	s_nop 0
	v_addc_co_u32_e32 v5, vcc, 0, v13, vcc
	s_waitcnt lgkmcnt(0)
	global_store_dwordx4 v[4:5], v[8:11], off
	ds_read_b128 v[4:7], v1 offset:4096
	ds_read_b128 v[8:11], v1 offset:5120
	v_add_co_u32_e32 v14, vcc, s0, v12
	s_mov_b32 s0, 0x50000
	s_nop 0
	v_addc_co_u32_e32 v15, vcc, 0, v13, vcc
	s_waitcnt lgkmcnt(1)
	global_store_dwordx4 v[14:15], v[4:7], off
	s_nop 1
	v_add_co_u32_e32 v4, vcc, s0, v12
	s_mov_b32 s0, 0x60000
	s_nop 0
	v_addc_co_u32_e32 v5, vcc, 0, v13, vcc
	s_waitcnt lgkmcnt(0)
	global_store_dwordx4 v[4:5], v[8:11], off
	ds_read_b128 v[4:7], v1 offset:6144
	ds_read_b128 v[8:11], v1 offset:7168
	v_add_co_u32_e32 v14, vcc, s0, v12
	s_mov_b32 s0, 0x70000
	s_nop 0
	v_addc_co_u32_e32 v15, vcc, 0, v13, vcc
	s_waitcnt lgkmcnt(1)
	global_store_dwordx4 v[14:15], v[4:7], off
	s_nop 1
	v_add_co_u32_e32 v4, vcc, s0, v12
	s_mov_b32 s0, 0x80000
	s_nop 0
	v_addc_co_u32_e32 v5, vcc, 0, v13, vcc
	s_waitcnt lgkmcnt(0)
	global_store_dwordx4 v[4:5], v[8:11], off
	ds_read_b128 v[4:7], v1 offset:8192
	ds_read_b128 v[8:11], v1 offset:9216
	v_add_co_u32_e32 v14, vcc, s0, v12
	s_mov_b32 s0, 0x90000
	s_nop 0
	v_addc_co_u32_e32 v15, vcc, 0, v13, vcc
	s_waitcnt lgkmcnt(1)
	global_store_dwordx4 v[14:15], v[4:7], off
	s_nop 1
	v_add_co_u32_e32 v4, vcc, s0, v12
	s_mov_b32 s0, 0xa0000
	s_nop 0
	v_addc_co_u32_e32 v5, vcc, 0, v13, vcc
	s_waitcnt lgkmcnt(0)
	global_store_dwordx4 v[4:5], v[8:11], off
	ds_read_b128 v[4:7], v1 offset:10240
	ds_read_b128 v[8:11], v1 offset:11264
	v_add_co_u32_e32 v14, vcc, s0, v12
	s_mov_b32 s0, 0xb0000
	s_nop 0
	v_addc_co_u32_e32 v15, vcc, 0, v13, vcc
	s_waitcnt lgkmcnt(1)
	global_store_dwordx4 v[14:15], v[4:7], off
	s_nop 1
	v_add_co_u32_e32 v4, vcc, s0, v12
	s_mov_b32 s0, 0xc0000
	s_nop 0
	v_addc_co_u32_e32 v5, vcc, 0, v13, vcc
	s_waitcnt lgkmcnt(0)
	global_store_dwordx4 v[4:5], v[8:11], off
	ds_read_b128 v[4:7], v1 offset:12288
	ds_read_b128 v[8:11], v1 offset:13312
	v_add_co_u32_e32 v14, vcc, s0, v12
	s_mov_b32 s0, 0xd0000
	s_nop 0
	v_addc_co_u32_e32 v15, vcc, 0, v13, vcc
	s_waitcnt lgkmcnt(1)
	global_store_dwordx4 v[14:15], v[4:7], off
	s_nop 1
	v_add_co_u32_e32 v4, vcc, s0, v12
	s_add_i32 s0, s7, 0x200
	s_nop 0
	v_addc_co_u32_e32 v5, vcc, 0, v13, vcc
	s_waitcnt lgkmcnt(0)
	global_store_dwordx4 v[4:5], v[8:11], off
	ds_read_b128 v[4:7], v1 offset:14336
	ds_read_b128 v[8:11], v1 offset:15360
	v_add_co_u32_e32 v14, vcc, 0xe0000, v12
	s_cmpk_lt_i32 s7, 0x1c00
	s_nop 0
	v_addc_co_u32_e32 v15, vcc, 0, v13, vcc
	s_waitcnt lgkmcnt(1)
	global_store_dwordx4 v[14:15], v[4:7], off
	s_mov_b32 s7, s0
	s_nop 0
	v_add_co_u32_e32 v4, vcc, 0xf0000, v12
	s_nop 1
	v_addc_co_u32_e32 v5, vcc, 0, v13, vcc
	s_waitcnt lgkmcnt(0)
	global_store_dwordx4 v[4:5], v[8:11], off
	s_cbranch_scc0 .LBB0_1506
